# merge GEMM: rho hook and GB epilogue issue all loads up front with counted vmcnt waits (no per-group vmcnt(0) round trips)
# speedup vs baseline: 1.0115x; 1.0115x over previous
;     __device__ __forceinline__ void mid(f32x4 (&acc)[2][2][4][2], const Unit& u, int wr, int wc, int fr, int fq) const {
;         int zero = 0; asm volatile("" : "+v"(zero));
;         const int row0 = u.pm * 256 + wr * 64 + fr + zero, col0 = u.pn * 256 + wc * 32 + 8 * fq;
;         const unsigned char* rp = (const unsigned char*)RHO + (size_t)row0 * D + col0;
;         u32x2 g0 = __builtin_nontemporal_load((const u32x2*)rp), g1 = __builtin_nontemporal_load((const u32x2*)(rp + 128));
; #pragma unroll
;         for (int im = 0; im < 8; ++im) { const int ai = im >> 2, m = im & 3; u32x2 n0 = g0, n1 = g1;
;             if (im < 7) { const unsigned char* np = rp + (size_t)(((im + 1) >> 2) * 128 + ((im + 1) & 3) * 16) * D; n0 = __builtin_nontemporal_load((const u32x2*)np); n1 = __builtin_nontemporal_load((const u32x2*)(np + 128)); }
;             asm volatile("" ::: "memory");
; #pragma unroll
;             for (int bj = 0; bj < 2; ++bj) { const u32x2 g = bj ? g1 : g0;
; #pragma unroll
;                 for (int n = 0; n < 2; ++n) { const unsigned gw_ = n ? g.y : g.x; const f32x2u lo_ = __builtin_amdgcn_cvt_pk_f32_fp8((int)gw_, false), hi_ = __builtin_amdgcn_cvt_pk_f32_fp8((int)gw_, true);
;                     acc[ai][bj][m][n][0] *= lo_.x; acc[ai][bj][m][n][1] *= lo_.y; acc[ai][bj][m][n][2] *= hi_.x; acc[ai][bj][m][n][3] *= hi_.y;
;                     asm volatile("" : "+v"(acc[ai][bj][m][n])); } }
;             asm volatile("" ::: "memory"); g0 = n0; g1 = n1; }
.LBB0_418:
	v_mov_b32_e32 v0, v1
	v_add_u32_e32 v2, v140, v0
	v_ashrrev_i32_e32 v3, 31, v2
	v_lshlrev_b64 v[2:3], 10, v[2:3]
	v_lshl_add_u64 v[2:3], v[138:139], 0, v[2:3]
	global_load_dwordx2 v[154:155], v[2:3], off nt
	global_load_dwordx2 v[156:157], v[2:3], off offset:128 nt
	s_mov_b64 s[100:101], 0x4000
	v_lshl_add_u64 v[142:143], v[2:3], 0, s[100:101]
	global_load_dwordx2 v[158:159], v[142:143], off nt
	global_load_dwordx2 v[160:161], v[142:143], off offset:128 nt
	s_mov_b64 s[100:101], 0x8000
	v_lshl_add_u64 v[142:143], v[2:3], 0, s[100:101]
	global_load_dwordx2 v[162:163], v[142:143], off nt
	global_load_dwordx2 v[164:165], v[142:143], off offset:128 nt
	s_mov_b64 s[100:101], 0xc000
	v_lshl_add_u64 v[142:143], v[2:3], 0, s[100:101]
	global_load_dwordx2 v[166:167], v[142:143], off nt
	global_load_dwordx2 v[168:169], v[142:143], off offset:128 nt
	s_mov_b64 s[100:101], 0x20000
	v_lshl_add_u64 v[142:143], v[2:3], 0, s[100:101]
	global_load_dwordx2 v[172:173], v[142:143], off nt
	global_load_dwordx2 v[174:175], v[142:143], off offset:128 nt
	s_mov_b64 s[100:101], 0x24000
	v_lshl_add_u64 v[142:143], v[2:3], 0, s[100:101]
	global_load_dwordx2 v[176:177], v[142:143], off nt
	global_load_dwordx2 v[178:179], v[142:143], off offset:128 nt
	s_mov_b64 s[100:101], 0x28000
	v_lshl_add_u64 v[142:143], v[2:3], 0, s[100:101]
	global_load_dwordx2 v[180:181], v[142:143], off nt
	global_load_dwordx2 v[182:183], v[142:143], off offset:128 nt
	s_mov_b64 s[100:101], 0x2c000
	v_lshl_add_u64 v[142:143], v[2:3], 0, s[100:101]
	global_load_dwordx2 v[184:185], v[142:143], off nt
	global_load_dwordx2 v[186:187], v[142:143], off offset:128 nt
	s_waitcnt vmcnt(15)
	v_cvt_pk_f32_fp8_e32 v[146:147], v154
	v_cvt_pk_f32_fp8_sdwa v[142:143], v154 src0_sel:WORD_1
	v_cvt_pk_f32_fp8_e32 v[2:3], v155
	v_cvt_pk_f32_fp8_sdwa v[154:155], v155 src0_sel:WORD_1
	v_pk_mul_f32 v[128:129], v[128:129], v[146:147]
	v_pk_mul_f32 v[130:131], v[130:131], v[142:143]
	v_pk_mul_f32 v[124:125], v[124:125], v[2:3]
	v_pk_mul_f32 v[126:127], v[126:127], v[154:155]
	s_waitcnt vmcnt(14)
	v_cvt_pk_f32_fp8_e32 v[146:147], v156
	v_cvt_pk_f32_fp8_sdwa v[142:143], v156 src0_sel:WORD_1
	v_cvt_pk_f32_fp8_e32 v[2:3], v157
	v_cvt_pk_f32_fp8_sdwa v[156:157], v157 src0_sel:WORD_1
	v_pk_mul_f32 v[120:121], v[120:121], v[146:147]
	v_pk_mul_f32 v[122:123], v[122:123], v[142:143]
	v_pk_mul_f32 v[112:113], v[112:113], v[2:3]
	v_pk_mul_f32 v[114:115], v[114:115], v[156:157]
	s_waitcnt vmcnt(13)
	v_cvt_pk_f32_fp8_e32 v[146:147], v158
	v_cvt_pk_f32_fp8_sdwa v[142:143], v158 src0_sel:WORD_1
	v_cvt_pk_f32_fp8_e32 v[2:3], v159
	v_cvt_pk_f32_fp8_sdwa v[158:159], v159 src0_sel:WORD_1
	v_pk_mul_f32 v[116:117], v[116:117], v[146:147]
	v_pk_mul_f32 v[118:119], v[118:119], v[142:143]
	v_pk_mul_f32 v[108:109], v[108:109], v[2:3]
	v_pk_mul_f32 v[110:111], v[110:111], v[158:159]
	s_waitcnt vmcnt(12)
	v_cvt_pk_f32_fp8_e32 v[146:147], v160
	v_cvt_pk_f32_fp8_sdwa v[142:143], v160 src0_sel:WORD_1
	v_cvt_pk_f32_fp8_e32 v[2:3], v161
	v_cvt_pk_f32_fp8_sdwa v[160:161], v161 src0_sel:WORD_1
	v_pk_mul_f32 v[104:105], v[104:105], v[146:147]
	v_pk_mul_f32 v[106:107], v[106:107], v[142:143]
	v_pk_mul_f32 v[96:97], v[96:97], v[2:3]
	v_pk_mul_f32 v[98:99], v[98:99], v[160:161]
	s_waitcnt vmcnt(11)
	v_cvt_pk_f32_fp8_e32 v[146:147], v162
	v_cvt_pk_f32_fp8_sdwa v[142:143], v162 src0_sel:WORD_1
	v_cvt_pk_f32_fp8_e32 v[2:3], v163
	v_cvt_pk_f32_fp8_sdwa v[162:163], v163 src0_sel:WORD_1
	v_pk_mul_f32 v[100:101], v[100:101], v[146:147]
	v_pk_mul_f32 v[102:103], v[102:103], v[142:143]
	v_pk_mul_f32 v[92:93], v[92:93], v[2:3]
	v_pk_mul_f32 v[94:95], v[94:95], v[162:163]
	s_waitcnt vmcnt(10)
	v_cvt_pk_f32_fp8_e32 v[146:147], v164
	v_cvt_pk_f32_fp8_sdwa v[142:143], v164 src0_sel:WORD_1
	v_cvt_pk_f32_fp8_e32 v[2:3], v165
	v_cvt_pk_f32_fp8_sdwa v[164:165], v165 src0_sel:WORD_1
	v_pk_mul_f32 v[88:89], v[88:89], v[146:147]
	v_pk_mul_f32 v[90:91], v[90:91], v[142:143]
	v_pk_mul_f32 v[80:81], v[80:81], v[2:3]
	v_pk_mul_f32 v[82:83], v[82:83], v[164:165]
	s_waitcnt vmcnt(9)
;     __device__ __forceinline__ void mid(f32x4 (&acc)[2][2][4][2], const Unit& u, int wr, int wc, int fr, int fq) const {
;     ...
;         for (int im = 0; im < 8; ++im) { const int ai = im >> 2, m = im & 3; u32x2 n0 = g0, n1 = g1;
;             if (im < 7) { const unsigned char* np = rp + (size_t)(((im + 1) >> 2) * 128 + ((im + 1) & 3) * 16) * D; n0 = __builtin_nontemporal_load((const u32x2*)np); n1 = __builtin_nontemporal_load((const u32x2*)(np + 128)); }
;             asm volatile("" ::: "memory");
; #pragma unroll
;             for (int bj = 0; bj < 2; ++bj) { const u32x2 g = bj ? g1 : g0;
; #pragma unroll
;                 for (int n = 0; n < 2; ++n) { const unsigned gw_ = n ? g.y : g.x; const f32x2u lo_ = __builtin_amdgcn_cvt_pk_f32_fp8((int)gw_, false), hi_ = __builtin_amdgcn_cvt_pk_f32_fp8((int)gw_, true);
;                     acc[ai][bj][m][n][0] *= lo_.x; acc[ai][bj][m][n][1] *= lo_.y; acc[ai][bj][m][n][2] *= hi_.x; acc[ai][bj][m][n][3] *= hi_.y;
;                     asm volatile("" : "+v"(acc[ai][bj][m][n])); } }
;             asm volatile("" ::: "memory"); g0 = n0; g1 = n1; }
	v_cvt_pk_f32_fp8_e32 v[146:147], v166
	v_cvt_pk_f32_fp8_sdwa v[142:143], v166 src0_sel:WORD_1
	v_cvt_pk_f32_fp8_e32 v[2:3], v167
	v_cvt_pk_f32_fp8_sdwa v[166:167], v167 src0_sel:WORD_1
	v_pk_mul_f32 v[84:85], v[84:85], v[146:147]
	v_pk_mul_f32 v[86:87], v[86:87], v[142:143]
	v_pk_mul_f32 v[76:77], v[76:77], v[2:3]
	v_pk_mul_f32 v[78:79], v[78:79], v[166:167]
	s_waitcnt vmcnt(8)
	v_cvt_pk_f32_fp8_e32 v[146:147], v168
	v_cvt_pk_f32_fp8_sdwa v[142:143], v168 src0_sel:WORD_1
	v_cvt_pk_f32_fp8_e32 v[2:3], v169
	v_cvt_pk_f32_fp8_sdwa v[168:169], v169 src0_sel:WORD_1
	v_pk_mul_f32 v[64:65], v[64:65], v[146:147]
	v_pk_mul_f32 v[66:67], v[66:67], v[142:143]
	v_pk_mul_f32 v[60:61], v[60:61], v[2:3]
	v_pk_mul_f32 v[62:63], v[62:63], v[168:169]
	s_waitcnt vmcnt(7)
	v_cvt_pk_f32_fp8_e32 v[146:147], v172
	v_cvt_pk_f32_fp8_sdwa v[142:143], v172 src0_sel:WORD_1
	v_cvt_pk_f32_fp8_e32 v[2:3], v173
	v_cvt_pk_f32_fp8_sdwa v[172:173], v173 src0_sel:WORD_1
	v_pk_mul_f32 v[72:73], v[72:73], v[146:147]
	v_pk_mul_f32 v[74:75], v[74:75], v[142:143]
	v_pk_mul_f32 v[68:69], v[68:69], v[2:3]
	v_pk_mul_f32 v[70:71], v[70:71], v[172:173]
	s_waitcnt vmcnt(6)
	v_cvt_pk_f32_fp8_e32 v[146:147], v174
	v_cvt_pk_f32_fp8_sdwa v[142:143], v174 src0_sel:WORD_1
	v_cvt_pk_f32_fp8_e32 v[2:3], v175
	v_cvt_pk_f32_fp8_sdwa v[174:175], v175 src0_sel:WORD_1
	v_pk_mul_f32 v[56:57], v[56:57], v[146:147]
	v_pk_mul_f32 v[58:59], v[58:59], v[142:143]
	v_pk_mul_f32 v[48:49], v[48:49], v[2:3]
	v_pk_mul_f32 v[50:51], v[50:51], v[174:175]
	s_waitcnt vmcnt(5)
	v_cvt_pk_f32_fp8_e32 v[146:147], v176
	v_cvt_pk_f32_fp8_sdwa v[142:143], v176 src0_sel:WORD_1
	v_cvt_pk_f32_fp8_e32 v[2:3], v177
	v_cvt_pk_f32_fp8_sdwa v[176:177], v177 src0_sel:WORD_1
	v_pk_mul_f32 v[52:53], v[52:53], v[146:147]
	v_pk_mul_f32 v[54:55], v[54:55], v[142:143]
	v_pk_mul_f32 v[44:45], v[44:45], v[2:3]
	v_pk_mul_f32 v[46:47], v[46:47], v[176:177]
	s_waitcnt vmcnt(4)
	v_cvt_pk_f32_fp8_e32 v[146:147], v178
	v_cvt_pk_f32_fp8_sdwa v[142:143], v178 src0_sel:WORD_1
	v_cvt_pk_f32_fp8_e32 v[2:3], v179
	v_cvt_pk_f32_fp8_sdwa v[178:179], v179 src0_sel:WORD_1
	v_pk_mul_f32 v[40:41], v[40:41], v[146:147]
	v_pk_mul_f32 v[42:43], v[42:43], v[142:143]
	v_pk_mul_f32 v[32:33], v[32:33], v[2:3]
	v_pk_mul_f32 v[34:35], v[34:35], v[178:179]
	s_waitcnt vmcnt(3)
	v_cvt_pk_f32_fp8_e32 v[146:147], v180
	v_cvt_pk_f32_fp8_sdwa v[142:143], v180 src0_sel:WORD_1
	v_cvt_pk_f32_fp8_e32 v[2:3], v181
	v_cvt_pk_f32_fp8_sdwa v[180:181], v181 src0_sel:WORD_1
	v_pk_mul_f32 v[36:37], v[36:37], v[146:147]
	v_pk_mul_f32 v[38:39], v[38:39], v[142:143]
	v_pk_mul_f32 v[28:29], v[28:29], v[2:3]
	v_pk_mul_f32 v[30:31], v[30:31], v[180:181]
	s_waitcnt vmcnt(2)
	v_cvt_pk_f32_fp8_e32 v[146:147], v182
	v_cvt_pk_f32_fp8_sdwa v[142:143], v182 src0_sel:WORD_1
	v_cvt_pk_f32_fp8_e32 v[2:3], v183
	v_cvt_pk_f32_fp8_sdwa v[182:183], v183 src0_sel:WORD_1
	v_pk_mul_f32 v[24:25], v[24:25], v[146:147]
	v_pk_mul_f32 v[26:27], v[26:27], v[142:143]
	v_pk_mul_f32 v[16:17], v[16:17], v[2:3]
	v_pk_mul_f32 v[18:19], v[18:19], v[182:183]
	s_waitcnt vmcnt(1)
	v_cvt_pk_f32_fp8_e32 v[146:147], v184
	v_cvt_pk_f32_fp8_sdwa v[142:143], v184 src0_sel:WORD_1
	v_cvt_pk_f32_fp8_e32 v[2:3], v185
	v_cvt_pk_f32_fp8_sdwa v[184:185], v185 src0_sel:WORD_1
	v_pk_mul_f32 v[20:21], v[20:21], v[146:147]
	v_pk_mul_f32 v[22:23], v[22:23], v[142:143]
	v_pk_mul_f32 v[12:13], v[12:13], v[2:3]
	v_pk_mul_f32 v[14:15], v[14:15], v[184:185]
	s_waitcnt vmcnt(0)
	v_cvt_pk_f32_fp8_e32 v[146:147], v186
	v_cvt_pk_f32_fp8_sdwa v[142:143], v186 src0_sel:WORD_1
	v_cvt_pk_f32_fp8_e32 v[2:3], v187
	v_cvt_pk_f32_fp8_sdwa v[186:187], v187 src0_sel:WORD_1
	v_pk_mul_f32 v[8:9], v[8:9], v[146:147]
	v_pk_mul_f32 v[10:11], v[10:11], v[142:143]
	v_pk_mul_f32 v[4:5], v[4:5], v[2:3]
	v_pk_mul_f32 v[6:7], v[6:7], v[186:187]
	s_nop 0

; __device__ __forceinline__ unsigned cvt_pk_bf16(float lo, float hi) { f32x2_t v = {lo, hi}; bf16x2_t r = __builtin_convertvector(v, bf16x2_t); return __builtin_bit_cast(unsigned, r); }
; __device__ __forceinline__ float bf_lo(unsigned u) { return __uint_as_float(u << 16); }
; __device__ __forceinline__ float bf_hi(unsigned u) { return __uint_as_float(u & 0xffff0000u); }
;     __device__ __forceinline__ void operator()(const f32x4 (&acc)[2][2][4][2], const Unit& u, int wr, int wc, int fr, int fq) const {
;         int zero = 0; asm volatile("" : "+v"(zero));
;         const int row0 = u.pm * 256 + wr * 64 + fr + zero, col0 = u.pn * 256 + wc * 32 + 8 * fq;
;         const bf16_t* gp = GB + (size_t)row0 * D + col0; bf16_t* op = O + (size_t)row0 * D + col0;
;         u32x4 g0 = __builtin_nontemporal_load((const u32x4*)gp), g1 = __builtin_nontemporal_load((const u32x4*)(gp + 128));
; #pragma unroll
;         for (int im = 0; im < 8; ++im) { const int ai = im >> 2, m = im & 3; u32x4 n0 = g0, n1 = g1; const size_t ro = (size_t)(ai * 128 + m * 16) * D;
;             if (im < 7) { const bf16_t* np = gp + (size_t)(((im + 1) >> 2) * 128 + ((im + 1) & 3) * 16) * D; n0 = __builtin_nontemporal_load((const u32x4*)np); n1 = __builtin_nontemporal_load((const u32x4*)(np + 128)); }
;             asm volatile("" ::: "memory");
; #pragma unroll
;             for (int bj = 0; bj < 2; ++bj) { const u32x4 g = bj ? g1 : g0;
;                 const f32x4 v0 = acc[ai][bj][m][0] * (1.0f / W8_SCALE), v1 = acc[ai][bj][m][1] * (1.0f / W8_SCALE);
;                 u32x4 w; w.x = cvt_pk_bf16(v0[0] * bf_lo(g.x), v0[1] * bf_hi(g.x)); w.y = cvt_pk_bf16(v0[2] * bf_lo(g.y), v0[3] * bf_hi(g.y));
;                 w.z = cvt_pk_bf16(v1[0] * bf_lo(g.z), v1[1] * bf_hi(g.z)); w.w = cvt_pk_bf16(v1[2] * bf_lo(g.w), v1[3] * bf_hi(g.w));
;                 *(u32x4*)(op + ro + bj * 128) = w; }
;             asm volatile("" ::: "memory"); g0 = n0; g1 = n1; }
.LBB0_421:
.LBB0_422:
	s_and_b64 vcc, exec, s[18:19]
	s_cbranch_vccz .LBB0_424
	s_barrier
.LBB0_424:
	v_mov_b32_e32 v0, v1
	s_lshl_b32 s24, s67, 8
	v_ashrrev_i32_e32 v137, 31, v136
	v_add3_u32 v2, s24, v149, v0
	v_ashrrev_i32_e32 v3, 31, v2
	v_lshlrev_b64 v[2:3], 11, v[2:3]
	v_lshlrev_b64 v[142:143], 1, v[136:137]
	v_lshl_add_u64 v[236:237], s[86:87], 0, v[2:3]
	v_lshl_add_u64 v[236:237], v[236:237], 0, v[142:143]
	v_lshl_add_u64 v[238:239], s[90:91], 0, v[2:3]
	v_lshl_add_u64 v[238:239], v[238:239], 0, v[142:143]
	global_load_dwordx4 v[172:175], v[236:237], off nt
	global_load_dwordx4 v[176:179], v[236:237], off offset:256 nt
	s_mov_b64 s[100:101], 0x8000
	v_lshl_add_u64 v[240:241], v[236:237], 0, s[100:101]
	global_load_dwordx4 v[180:183], v[240:241], off nt
	global_load_dwordx4 v[184:187], v[240:241], off offset:256 nt
	s_mov_b64 s[100:101], 0x10000
	v_lshl_add_u64 v[240:241], v[236:237], 0, s[100:101]
	global_load_dwordx4 v[188:191], v[240:241], off nt
	global_load_dwordx4 v[192:195], v[240:241], off offset:256 nt
	s_mov_b64 s[100:101], 0x18000
	v_lshl_add_u64 v[240:241], v[236:237], 0, s[100:101]
	global_load_dwordx4 v[196:199], v[240:241], off nt
	global_load_dwordx4 v[200:203], v[240:241], off offset:256 nt
	s_mov_b64 s[100:101], 0x40000
	v_lshl_add_u64 v[240:241], v[236:237], 0, s[100:101]
	global_load_dwordx4 v[204:207], v[240:241], off nt
	global_load_dwordx4 v[208:211], v[240:241], off offset:256 nt
	s_mov_b64 s[100:101], 0x48000
	v_lshl_add_u64 v[240:241], v[236:237], 0, s[100:101]
	global_load_dwordx4 v[212:215], v[240:241], off nt
	global_load_dwordx4 v[216:219], v[240:241], off offset:256 nt
	s_mov_b64 s[100:101], 0x50000
	v_lshl_add_u64 v[240:241], v[236:237], 0, s[100:101]
	global_load_dwordx4 v[220:223], v[240:241], off nt
	global_load_dwordx4 v[224:227], v[240:241], off offset:256 nt
	s_mov_b64 s[100:101], 0x58000
	v_lshl_add_u64 v[240:241], v[236:237], 0, s[100:101]
	global_load_dwordx4 v[228:231], v[240:241], off nt
	global_load_dwordx4 v[232:235], v[240:241], off offset:256 nt
	v_pk_mul_f32 v[4:5], v[4:5], s[20:21] op_sel_hi:[1,0]
	v_pk_mul_f32 v[6:7], v[6:7], s[20:21] op_sel_hi:[1,0]
	v_pk_mul_f32 v[8:9], v[8:9], s[20:21] op_sel_hi:[1,0]
	v_pk_mul_f32 v[10:11], v[10:11], s[20:21] op_sel_hi:[1,0]
	v_pk_mul_f32 v[12:13], v[12:13], s[20:21] op_sel_hi:[1,0]
	v_pk_mul_f32 v[14:15], v[14:15], s[20:21] op_sel_hi:[1,0]
	v_pk_mul_f32 v[16:17], v[16:17], s[20:21] op_sel_hi:[1,0]
	v_pk_mul_f32 v[18:19], v[18:19], s[20:21] op_sel_hi:[1,0]
	v_pk_mul_f32 v[20:21], v[20:21], s[20:21] op_sel_hi:[1,0]
	v_pk_mul_f32 v[22:23], v[22:23], s[20:21] op_sel_hi:[1,0]
	v_pk_mul_f32 v[24:25], v[24:25], s[20:21] op_sel_hi:[1,0]
	v_pk_mul_f32 v[26:27], v[26:27], s[20:21] op_sel_hi:[1,0]
	v_pk_mul_f32 v[28:29], v[28:29], s[20:21] op_sel_hi:[1,0]
	v_pk_mul_f32 v[30:31], v[30:31], s[20:21] op_sel_hi:[1,0]
	v_pk_mul_f32 v[32:33], v[32:33], s[20:21] op_sel_hi:[1,0]
	v_pk_mul_f32 v[34:35], v[34:35], s[20:21] op_sel_hi:[1,0]
	v_pk_mul_f32 v[36:37], v[36:37], s[20:21] op_sel_hi:[1,0]
	v_pk_mul_f32 v[38:39], v[38:39], s[20:21] op_sel_hi:[1,0]
	v_pk_mul_f32 v[40:41], v[40:41], s[20:21] op_sel_hi:[1,0]
	v_pk_mul_f32 v[42:43], v[42:43], s[20:21] op_sel_hi:[1,0]
	v_pk_mul_f32 v[44:45], v[44:45], s[20:21] op_sel_hi:[1,0]
	v_pk_mul_f32 v[46:47], v[46:47], s[20:21] op_sel_hi:[1,0]
	v_pk_mul_f32 v[48:49], v[48:49], s[20:21] op_sel_hi:[1,0]
	v_pk_mul_f32 v[50:51], v[50:51], s[20:21] op_sel_hi:[1,0]
	v_pk_mul_f32 v[52:53], v[52:53], s[20:21] op_sel_hi:[1,0]
	v_pk_mul_f32 v[54:55], v[54:55], s[20:21] op_sel_hi:[1,0]
	v_pk_mul_f32 v[56:57], v[56:57], s[20:21] op_sel_hi:[1,0]
	v_pk_mul_f32 v[58:59], v[58:59], s[20:21] op_sel_hi:[1,0]
	v_pk_mul_f32 v[60:61], v[60:61], s[20:21] op_sel_hi:[1,0]
	v_pk_mul_f32 v[62:63], v[62:63], s[20:21] op_sel_hi:[1,0]
	v_pk_mul_f32 v[64:65], v[64:65], s[20:21] op_sel_hi:[1,0]
	v_pk_mul_f32 v[66:67], v[66:67], s[20:21] op_sel_hi:[1,0]
	v_pk_mul_f32 v[68:69], v[68:69], s[20:21] op_sel_hi:[1,0]
	v_pk_mul_f32 v[70:71], v[70:71], s[20:21] op_sel_hi:[1,0]
	v_pk_mul_f32 v[72:73], v[72:73], s[20:21] op_sel_hi:[1,0]
	v_pk_mul_f32 v[74:75], v[74:75], s[20:21] op_sel_hi:[1,0]
	v_pk_mul_f32 v[76:77], v[76:77], s[20:21] op_sel_hi:[1,0]
	v_pk_mul_f32 v[78:79], v[78:79], s[20:21] op_sel_hi:[1,0]
	v_pk_mul_f32 v[80:81], v[80:81], s[20:21] op_sel_hi:[1,0]
	v_pk_mul_f32 v[82:83], v[82:83], s[20:21] op_sel_hi:[1,0]
	v_pk_mul_f32 v[84:85], v[84:85], s[20:21] op_sel_hi:[1,0]
	v_pk_mul_f32 v[86:87], v[86:87], s[20:21] op_sel_hi:[1,0]
	v_pk_mul_f32 v[88:89], v[88:89], s[20:21] op_sel_hi:[1,0]
	v_pk_mul_f32 v[90:91], v[90:91], s[20:21] op_sel_hi:[1,0]
	v_pk_mul_f32 v[92:93], v[92:93], s[20:21] op_sel_hi:[1,0]
	v_pk_mul_f32 v[94:95], v[94:95], s[20:21] op_sel_hi:[1,0]
	v_pk_mul_f32 v[96:97], v[96:97], s[20:21] op_sel_hi:[1,0]
	v_pk_mul_f32 v[98:99], v[98:99], s[20:21] op_sel_hi:[1,0]
	v_pk_mul_f32 v[100:101], v[100:101], s[20:21] op_sel_hi:[1,0]
	v_pk_mul_f32 v[102:103], v[102:103], s[20:21] op_sel_hi:[1,0]
	v_pk_mul_f32 v[104:105], v[104:105], s[20:21] op_sel_hi:[1,0]
	v_pk_mul_f32 v[106:107], v[106:107], s[20:21] op_sel_hi:[1,0]
	v_pk_mul_f32 v[108:109], v[108:109], s[20:21] op_sel_hi:[1,0]
	v_pk_mul_f32 v[110:111], v[110:111], s[20:21] op_sel_hi:[1,0]
	v_pk_mul_f32 v[112:113], v[112:113], s[20:21] op_sel_hi:[1,0]
	v_pk_mul_f32 v[114:115], v[114:115], s[20:21] op_sel_hi:[1,0]
	v_pk_mul_f32 v[116:117], v[116:117], s[20:21] op_sel_hi:[1,0]
	v_pk_mul_f32 v[118:119], v[118:119], s[20:21] op_sel_hi:[1,0]
	v_pk_mul_f32 v[120:121], v[120:121], s[20:21] op_sel_hi:[1,0]
	v_pk_mul_f32 v[122:123], v[122:123], s[20:21] op_sel_hi:[1,0]
	v_pk_mul_f32 v[124:125], v[124:125], s[20:21] op_sel_hi:[1,0]
	v_pk_mul_f32 v[126:127], v[126:127], s[20:21] op_sel_hi:[1,0]
	v_pk_mul_f32 v[128:129], v[128:129], s[20:21] op_sel_hi:[1,0]
	v_pk_mul_f32 v[130:131], v[130:131], s[20:21] op_sel_hi:[1,0]
	s_waitcnt vmcnt(15)
; __device__ __forceinline__ unsigned cvt_pk_bf16(float lo, float hi) { f32x2_t v = {lo, hi}; bf16x2_t r = __builtin_convertvector(v, bf16x2_t); return __builtin_bit_cast(unsigned, r); }
; __device__ __forceinline__ float bf_lo(unsigned u) { return __uint_as_float(u << 16); }
; __device__ __forceinline__ float bf_hi(unsigned u) { return __uint_as_float(u & 0xffff0000u); }
;     __device__ __forceinline__ void operator()(const f32x4 (&acc)[2][2][4][2], const Unit& u, int wr, int wc, int fr, int fq) const {
;     ...
;         for (int im = 0; im < 8; ++im) { const int ai = im >> 2, m = im & 3; u32x4 n0 = g0, n1 = g1; const size_t ro = (size_t)(ai * 128 + m * 16) * D;
;             if (im < 7) { const bf16_t* np = gp + (size_t)(((im + 1) >> 2) * 128 + ((im + 1) & 3) * 16) * D; n0 = __builtin_nontemporal_load((const u32x4*)np); n1 = __builtin_nontemporal_load((const u32x4*)(np + 128)); }
;             asm volatile("" ::: "memory");
; #pragma unroll
;             for (int bj = 0; bj < 2; ++bj) { const u32x4 g = bj ? g1 : g0;
;                 const f32x4 v0 = acc[ai][bj][m][0] * (1.0f / W8_SCALE), v1 = acc[ai][bj][m][1] * (1.0f / W8_SCALE);
;                 u32x4 w; w.x = cvt_pk_bf16(v0[0] * bf_lo(g.x), v0[1] * bf_hi(g.x)); w.y = cvt_pk_bf16(v0[2] * bf_lo(g.y), v0[3] * bf_hi(g.y));
;                 w.z = cvt_pk_bf16(v1[0] * bf_lo(g.z), v1[1] * bf_hi(g.z)); w.w = cvt_pk_bf16(v1[2] * bf_lo(g.w), v1[3] * bf_hi(g.w));
;                 *(u32x4*)(op + ro + bj * 128) = w; }
;             asm volatile("" ::: "memory"); g0 = n0; g1 = n1; }
	v_lshlrev_b32_e32 v154, 16, v172
	v_and_b32_e32 v155, 0xffff0000, v172
	v_lshlrev_b32_e32 v156, 16, v173
	v_and_b32_e32 v157, 0xffff0000, v173
	v_lshlrev_b32_e32 v158, 16, v174
	v_and_b32_e32 v159, 0xffff0000, v174
	v_lshlrev_b32_e32 v160, 16, v175
	v_and_b32_e32 v161, 0xffff0000, v175
	v_pk_mul_f32 v[128:129], v[128:129], v[154:155]
	v_pk_mul_f32 v[130:131], v[130:131], v[156:157]
	v_pk_mul_f32 v[124:125], v[124:125], v[158:159]
	v_pk_mul_f32 v[126:127], v[126:127], v[160:161]
	v_cvt_pk_bf16_f32 v128, v128, v129
	v_cvt_pk_bf16_f32 v129, v130, v131
	v_cvt_pk_bf16_f32 v130, v124, v125
	v_cvt_pk_bf16_f32 v131, v126, v127
	global_store_dwordx4 v[238:239], v[128:131], off
	s_waitcnt vmcnt(15)
	v_lshlrev_b32_e32 v162, 16, v176
	v_and_b32_e32 v163, 0xffff0000, v176
	v_lshlrev_b32_e32 v164, 16, v177
	v_and_b32_e32 v165, 0xffff0000, v177
	v_lshlrev_b32_e32 v166, 16, v178
	v_and_b32_e32 v167, 0xffff0000, v178
	v_lshlrev_b32_e32 v168, 16, v179
	v_and_b32_e32 v169, 0xffff0000, v179
	v_pk_mul_f32 v[120:121], v[120:121], v[162:163]
	v_pk_mul_f32 v[122:123], v[122:123], v[164:165]
	v_pk_mul_f32 v[112:113], v[112:113], v[166:167]
	v_pk_mul_f32 v[114:115], v[114:115], v[168:169]
	v_cvt_pk_bf16_f32 v120, v120, v121
	v_cvt_pk_bf16_f32 v121, v122, v123
	v_cvt_pk_bf16_f32 v122, v112, v113
	v_cvt_pk_bf16_f32 v123, v114, v115
	global_store_dwordx4 v[238:239], v[120:123], off offset:256
	s_mov_b64 s[100:101], 0x8000
	v_lshl_add_u64 v[242:243], v[238:239], 0, s[100:101]
	s_waitcnt vmcnt(15)
	v_lshlrev_b32_e32 v154, 16, v180
	v_and_b32_e32 v155, 0xffff0000, v180
	v_lshlrev_b32_e32 v156, 16, v181
	v_and_b32_e32 v157, 0xffff0000, v181
	v_lshlrev_b32_e32 v158, 16, v182
	v_and_b32_e32 v159, 0xffff0000, v182
	v_lshlrev_b32_e32 v160, 16, v183
	v_and_b32_e32 v161, 0xffff0000, v183
	v_pk_mul_f32 v[116:117], v[116:117], v[154:155]
	v_pk_mul_f32 v[118:119], v[118:119], v[156:157]
	v_pk_mul_f32 v[108:109], v[108:109], v[158:159]
	v_pk_mul_f32 v[110:111], v[110:111], v[160:161]
	v_cvt_pk_bf16_f32 v116, v116, v117
	v_cvt_pk_bf16_f32 v117, v118, v119
	v_cvt_pk_bf16_f32 v118, v108, v109
	v_cvt_pk_bf16_f32 v119, v110, v111
	global_store_dwordx4 v[242:243], v[116:119], off
	s_waitcnt vmcnt(15)
	v_lshlrev_b32_e32 v162, 16, v184
	v_and_b32_e32 v163, 0xffff0000, v184
	v_lshlrev_b32_e32 v164, 16, v185
	v_and_b32_e32 v165, 0xffff0000, v185
	v_lshlrev_b32_e32 v166, 16, v186
	v_and_b32_e32 v167, 0xffff0000, v186
	v_lshlrev_b32_e32 v168, 16, v187
	v_and_b32_e32 v169, 0xffff0000, v187
	v_pk_mul_f32 v[104:105], v[104:105], v[162:163]
	v_pk_mul_f32 v[106:107], v[106:107], v[164:165]
	v_pk_mul_f32 v[96:97], v[96:97], v[166:167]
	v_pk_mul_f32 v[98:99], v[98:99], v[168:169]
	v_cvt_pk_bf16_f32 v104, v104, v105
	v_cvt_pk_bf16_f32 v105, v106, v107
	v_cvt_pk_bf16_f32 v106, v96, v97
	v_cvt_pk_bf16_f32 v107, v98, v99
	global_store_dwordx4 v[242:243], v[104:107], off offset:256
	s_mov_b64 s[100:101], 0x10000
	v_lshl_add_u64 v[242:243], v[238:239], 0, s[100:101]
	s_waitcnt vmcnt(15)
	v_lshlrev_b32_e32 v154, 16, v188
	v_and_b32_e32 v155, 0xffff0000, v188
	v_lshlrev_b32_e32 v156, 16, v189
	v_and_b32_e32 v157, 0xffff0000, v189
	v_lshlrev_b32_e32 v158, 16, v190
	v_and_b32_e32 v159, 0xffff0000, v190
	v_lshlrev_b32_e32 v160, 16, v191
	v_and_b32_e32 v161, 0xffff0000, v191
	v_pk_mul_f32 v[100:101], v[100:101], v[154:155]
	v_pk_mul_f32 v[102:103], v[102:103], v[156:157]
	v_pk_mul_f32 v[92:93], v[92:93], v[158:159]
	v_pk_mul_f32 v[94:95], v[94:95], v[160:161]
	v_cvt_pk_bf16_f32 v100, v100, v101
	v_cvt_pk_bf16_f32 v101, v102, v103
	v_cvt_pk_bf16_f32 v102, v92, v93
	v_cvt_pk_bf16_f32 v103, v94, v95
	global_store_dwordx4 v[242:243], v[100:103], off
	s_waitcnt vmcnt(15)
	v_lshlrev_b32_e32 v162, 16, v192
	v_and_b32_e32 v163, 0xffff0000, v192
	v_lshlrev_b32_e32 v164, 16, v193
	v_and_b32_e32 v165, 0xffff0000, v193
	v_lshlrev_b32_e32 v166, 16, v194
	v_and_b32_e32 v167, 0xffff0000, v194
	v_lshlrev_b32_e32 v168, 16, v195
	v_and_b32_e32 v169, 0xffff0000, v195
	v_pk_mul_f32 v[88:89], v[88:89], v[162:163]
	v_pk_mul_f32 v[90:91], v[90:91], v[164:165]
	v_pk_mul_f32 v[80:81], v[80:81], v[166:167]
	v_pk_mul_f32 v[82:83], v[82:83], v[168:169]
	v_cvt_pk_bf16_f32 v88, v88, v89
	v_cvt_pk_bf16_f32 v89, v90, v91
	v_cvt_pk_bf16_f32 v90, v80, v81
	v_cvt_pk_bf16_f32 v91, v82, v83
	global_store_dwordx4 v[242:243], v[88:91], off offset:256
	s_mov_b64 s[100:101], 0x18000
	v_lshl_add_u64 v[242:243], v[238:239], 0, s[100:101]
	s_waitcnt vmcnt(15)
	v_lshlrev_b32_e32 v154, 16, v196
	v_and_b32_e32 v155, 0xffff0000, v196
	v_lshlrev_b32_e32 v156, 16, v197
	v_and_b32_e32 v157, 0xffff0000, v197
	v_lshlrev_b32_e32 v158, 16, v198
	v_and_b32_e32 v159, 0xffff0000, v198
	v_lshlrev_b32_e32 v160, 16, v199
	v_and_b32_e32 v161, 0xffff0000, v199
	v_pk_mul_f32 v[84:85], v[84:85], v[154:155]
	v_pk_mul_f32 v[86:87], v[86:87], v[156:157]
	v_pk_mul_f32 v[76:77], v[76:77], v[158:159]
	v_pk_mul_f32 v[78:79], v[78:79], v[160:161]
	v_cvt_pk_bf16_f32 v84, v84, v85
	v_cvt_pk_bf16_f32 v85, v86, v87
	v_cvt_pk_bf16_f32 v86, v76, v77
	v_cvt_pk_bf16_f32 v87, v78, v79
	global_store_dwordx4 v[242:243], v[84:87], off
	s_waitcnt vmcnt(15)
	v_lshlrev_b32_e32 v162, 16, v200
	v_and_b32_e32 v163, 0xffff0000, v200
	v_lshlrev_b32_e32 v164, 16, v201
	v_and_b32_e32 v165, 0xffff0000, v201
	v_lshlrev_b32_e32 v166, 16, v202
	v_and_b32_e32 v167, 0xffff0000, v202
	v_lshlrev_b32_e32 v168, 16, v203
	v_and_b32_e32 v169, 0xffff0000, v203
	v_pk_mul_f32 v[64:65], v[64:65], v[162:163]
	v_pk_mul_f32 v[66:67], v[66:67], v[164:165]
	v_pk_mul_f32 v[60:61], v[60:61], v[166:167]
	v_pk_mul_f32 v[62:63], v[62:63], v[168:169]
	v_cvt_pk_bf16_f32 v64, v64, v65
	v_cvt_pk_bf16_f32 v65, v66, v67
	v_cvt_pk_bf16_f32 v66, v60, v61
	v_cvt_pk_bf16_f32 v67, v62, v63
	global_store_dwordx4 v[242:243], v[64:67], off offset:256
	s_mov_b64 s[100:101], 0x40000
	v_lshl_add_u64 v[242:243], v[238:239], 0, s[100:101]
	s_waitcnt vmcnt(15)
; __device__ __forceinline__ unsigned cvt_pk_bf16(float lo, float hi) { f32x2_t v = {lo, hi}; bf16x2_t r = __builtin_convertvector(v, bf16x2_t); return __builtin_bit_cast(unsigned, r); }
; #define PG8_BAR __builtin_amdgcn_s_barrier()
; __device__ __forceinline__ float bf_lo(unsigned u) { return __uint_as_float(u << 16); }
; __device__ __forceinline__ float bf_hi(unsigned u) { return __uint_as_float(u & 0xffff0000u); }
; template <class Epi, class Sched, bool ALIGN_EPI = false, bool SP2 = false, bool F8 = false>
; __device__ __forceinline__ void gemm_phase(PG8_LAS unsigned char* lds, const Gemm g, const Sched& S, const Epi& E) {
;     ...
;         if (!has_next) break;
; #pragma unroll
;         for (int a = 0; a < 2; ++a)
; #pragma unroll
;             for (int b = 0; b < 2; ++b)
; #pragma unroll
;                 for (int m = 0; m < 4; ++m)
; #pragma unroll
;                     for (int n = 0; n < 2; ++n) acc[a][b][m][n] = (f32x4){0.f, 0.f, 0.f, 0.f};
;         cur = nxt; cA = nA; cB = nB; ++ui;
;         if constexpr (ALIGN_EPI) { if (wr == 1) PG8_BAR; }
;     __device__ __forceinline__ void operator()(const f32x4 (&acc)[2][2][4][2], const Unit& u, int wr, int wc, int fr, int fq) const {
;     ...
;         for (int im = 0; im < 8; ++im) { const int ai = im >> 2, m = im & 3; u32x4 n0 = g0, n1 = g1; const size_t ro = (size_t)(ai * 128 + m * 16) * D;
;             if (im < 7) { const bf16_t* np = gp + (size_t)(((im + 1) >> 2) * 128 + ((im + 1) & 3) * 16) * D; n0 = __builtin_nontemporal_load((const u32x4*)np); n1 = __builtin_nontemporal_load((const u32x4*)(np + 128)); }
;             asm volatile("" ::: "memory");
; #pragma unroll
;             for (int bj = 0; bj < 2; ++bj) { const u32x4 g = bj ? g1 : g0;
;                 const f32x4 v0 = acc[ai][bj][m][0] * (1.0f / W8_SCALE), v1 = acc[ai][bj][m][1] * (1.0f / W8_SCALE);
;                 u32x4 w; w.x = cvt_pk_bf16(v0[0] * bf_lo(g.x), v0[1] * bf_hi(g.x)); w.y = cvt_pk_bf16(v0[2] * bf_lo(g.y), v0[3] * bf_hi(g.y));
;                 w.z = cvt_pk_bf16(v1[0] * bf_lo(g.z), v1[1] * bf_hi(g.z)); w.w = cvt_pk_bf16(v1[2] * bf_lo(g.w), v1[3] * bf_hi(g.w));
;                 *(u32x4*)(op + ro + bj * 128) = w; }
;             asm volatile("" ::: "memory"); g0 = n0; g1 = n1; }
	v_lshlrev_b32_e32 v154, 16, v204
	v_and_b32_e32 v155, 0xffff0000, v204
	v_lshlrev_b32_e32 v156, 16, v205
	v_and_b32_e32 v157, 0xffff0000, v205
	v_lshlrev_b32_e32 v158, 16, v206
	v_and_b32_e32 v159, 0xffff0000, v206
	v_lshlrev_b32_e32 v160, 16, v207
	v_and_b32_e32 v161, 0xffff0000, v207
	v_pk_mul_f32 v[72:73], v[72:73], v[154:155]
	v_pk_mul_f32 v[74:75], v[74:75], v[156:157]
	v_pk_mul_f32 v[68:69], v[68:69], v[158:159]
	v_pk_mul_f32 v[70:71], v[70:71], v[160:161]
	v_cvt_pk_bf16_f32 v72, v72, v73
	v_cvt_pk_bf16_f32 v73, v74, v75
	v_cvt_pk_bf16_f32 v74, v68, v69
	v_cvt_pk_bf16_f32 v75, v70, v71
	global_store_dwordx4 v[242:243], v[72:75], off
	s_waitcnt vmcnt(15)
	v_lshlrev_b32_e32 v162, 16, v208
	v_and_b32_e32 v163, 0xffff0000, v208
	v_lshlrev_b32_e32 v164, 16, v209
	v_and_b32_e32 v165, 0xffff0000, v209
	v_lshlrev_b32_e32 v166, 16, v210
	v_and_b32_e32 v167, 0xffff0000, v210
	v_lshlrev_b32_e32 v168, 16, v211
	v_and_b32_e32 v169, 0xffff0000, v211
	v_pk_mul_f32 v[56:57], v[56:57], v[162:163]
	v_pk_mul_f32 v[58:59], v[58:59], v[164:165]
	v_pk_mul_f32 v[48:49], v[48:49], v[166:167]
	v_pk_mul_f32 v[50:51], v[50:51], v[168:169]
	v_cvt_pk_bf16_f32 v56, v56, v57
	v_cvt_pk_bf16_f32 v57, v58, v59
	v_cvt_pk_bf16_f32 v58, v48, v49
	v_cvt_pk_bf16_f32 v59, v50, v51
	global_store_dwordx4 v[242:243], v[56:59], off offset:256
	s_mov_b64 s[100:101], 0x48000
	v_lshl_add_u64 v[242:243], v[238:239], 0, s[100:101]
	s_waitcnt vmcnt(15)
	v_lshlrev_b32_e32 v154, 16, v212
	v_and_b32_e32 v155, 0xffff0000, v212
	v_lshlrev_b32_e32 v156, 16, v213
	v_and_b32_e32 v157, 0xffff0000, v213
	v_lshlrev_b32_e32 v158, 16, v214
	v_and_b32_e32 v159, 0xffff0000, v214
	v_lshlrev_b32_e32 v160, 16, v215
	v_and_b32_e32 v161, 0xffff0000, v215
	v_pk_mul_f32 v[52:53], v[52:53], v[154:155]
	v_pk_mul_f32 v[54:55], v[54:55], v[156:157]
	v_pk_mul_f32 v[44:45], v[44:45], v[158:159]
	v_pk_mul_f32 v[46:47], v[46:47], v[160:161]
	v_cvt_pk_bf16_f32 v52, v52, v53
	v_cvt_pk_bf16_f32 v53, v54, v55
	v_cvt_pk_bf16_f32 v54, v44, v45
	v_cvt_pk_bf16_f32 v55, v46, v47
	global_store_dwordx4 v[242:243], v[52:55], off
	s_waitcnt vmcnt(15)
	v_lshlrev_b32_e32 v162, 16, v216
	v_and_b32_e32 v163, 0xffff0000, v216
	v_lshlrev_b32_e32 v164, 16, v217
	v_and_b32_e32 v165, 0xffff0000, v217
	v_lshlrev_b32_e32 v166, 16, v218
	v_and_b32_e32 v167, 0xffff0000, v218
	v_lshlrev_b32_e32 v168, 16, v219
	v_and_b32_e32 v169, 0xffff0000, v219
	v_pk_mul_f32 v[40:41], v[40:41], v[162:163]
	v_pk_mul_f32 v[42:43], v[42:43], v[164:165]
	v_pk_mul_f32 v[32:33], v[32:33], v[166:167]
	v_pk_mul_f32 v[34:35], v[34:35], v[168:169]
	v_cvt_pk_bf16_f32 v40, v40, v41
	v_cvt_pk_bf16_f32 v41, v42, v43
	v_cvt_pk_bf16_f32 v42, v32, v33
	v_cvt_pk_bf16_f32 v43, v34, v35
	global_store_dwordx4 v[242:243], v[40:43], off offset:256
	s_mov_b64 s[100:101], 0x50000
	v_lshl_add_u64 v[242:243], v[238:239], 0, s[100:101]
	s_waitcnt vmcnt(15)
	v_lshlrev_b32_e32 v154, 16, v220
	v_and_b32_e32 v155, 0xffff0000, v220
	v_lshlrev_b32_e32 v156, 16, v221
	v_and_b32_e32 v157, 0xffff0000, v221
	v_lshlrev_b32_e32 v158, 16, v222
	v_and_b32_e32 v159, 0xffff0000, v222
	v_lshlrev_b32_e32 v160, 16, v223
	v_and_b32_e32 v161, 0xffff0000, v223
	v_pk_mul_f32 v[36:37], v[36:37], v[154:155]
	v_pk_mul_f32 v[38:39], v[38:39], v[156:157]
	v_pk_mul_f32 v[28:29], v[28:29], v[158:159]
	v_pk_mul_f32 v[30:31], v[30:31], v[160:161]
	v_cvt_pk_bf16_f32 v36, v36, v37
	v_cvt_pk_bf16_f32 v37, v38, v39
	v_cvt_pk_bf16_f32 v38, v28, v29
	v_cvt_pk_bf16_f32 v39, v30, v31
	global_store_dwordx4 v[242:243], v[36:39], off
	s_waitcnt vmcnt(15)
	v_lshlrev_b32_e32 v162, 16, v224
	v_and_b32_e32 v163, 0xffff0000, v224
	v_lshlrev_b32_e32 v164, 16, v225
	v_and_b32_e32 v165, 0xffff0000, v225
	v_lshlrev_b32_e32 v166, 16, v226
	v_and_b32_e32 v167, 0xffff0000, v226
	v_lshlrev_b32_e32 v168, 16, v227
	v_and_b32_e32 v169, 0xffff0000, v227
	v_pk_mul_f32 v[24:25], v[24:25], v[162:163]
	v_pk_mul_f32 v[26:27], v[26:27], v[164:165]
	v_pk_mul_f32 v[16:17], v[16:17], v[166:167]
	v_pk_mul_f32 v[18:19], v[18:19], v[168:169]
	v_cvt_pk_bf16_f32 v24, v24, v25
	v_cvt_pk_bf16_f32 v25, v26, v27
	v_cvt_pk_bf16_f32 v26, v16, v17
	v_cvt_pk_bf16_f32 v27, v18, v19
	global_store_dwordx4 v[242:243], v[24:27], off offset:256
	s_mov_b64 s[100:101], 0x58000
	v_lshl_add_u64 v[242:243], v[238:239], 0, s[100:101]
	s_waitcnt vmcnt(15)
	v_lshlrev_b32_e32 v154, 16, v228
	v_and_b32_e32 v155, 0xffff0000, v228
	v_lshlrev_b32_e32 v156, 16, v229
	v_and_b32_e32 v157, 0xffff0000, v229
	v_lshlrev_b32_e32 v158, 16, v230
	v_and_b32_e32 v159, 0xffff0000, v230
	v_lshlrev_b32_e32 v160, 16, v231
	v_and_b32_e32 v161, 0xffff0000, v231
	v_pk_mul_f32 v[20:21], v[20:21], v[154:155]
	v_pk_mul_f32 v[22:23], v[22:23], v[156:157]
	v_pk_mul_f32 v[12:13], v[12:13], v[158:159]
	v_pk_mul_f32 v[14:15], v[14:15], v[160:161]
	v_cvt_pk_bf16_f32 v20, v20, v21
	v_cvt_pk_bf16_f32 v21, v22, v23
	v_cvt_pk_bf16_f32 v22, v12, v13
	v_cvt_pk_bf16_f32 v23, v14, v15
	global_store_dwordx4 v[242:243], v[20:23], off
	s_waitcnt vmcnt(15)
	v_lshlrev_b32_e32 v162, 16, v232
	v_and_b32_e32 v163, 0xffff0000, v232
	v_lshlrev_b32_e32 v164, 16, v233
	v_and_b32_e32 v165, 0xffff0000, v233
	v_lshlrev_b32_e32 v166, 16, v234
	v_and_b32_e32 v167, 0xffff0000, v234
	v_lshlrev_b32_e32 v168, 16, v235
	v_and_b32_e32 v169, 0xffff0000, v235
	v_pk_mul_f32 v[8:9], v[8:9], v[162:163]
	v_pk_mul_f32 v[10:11], v[10:11], v[164:165]
	v_pk_mul_f32 v[4:5], v[4:5], v[166:167]
	v_pk_mul_f32 v[6:7], v[6:7], v[168:169]
	v_cvt_pk_bf16_f32 v8, v8, v9
	v_cvt_pk_bf16_f32 v9, v10, v11
	v_cvt_pk_bf16_f32 v10, v4, v5
	v_cvt_pk_bf16_f32 v11, v6, v7
	global_store_dwordx4 v[242:243], v[8:11], off offset:256
	s_and_b64 vcc, exec, s[0:1]
	s_mov_b64 s[0:1], -1
	s_cbranch_vccnz .LBB0_405
	s_andn2_b64 vcc, exec, s[10:11]
	s_cbranch_vccnz .LBB0_404
	s_barrier
	s_branch .LBB0_404

; __global__ void __launch_bounds__(NTHREADS, 2) fwd(Params p) {
	.amdhsa_kernel _ZN2mk3fwdENS_6ParamsE
		.amdhsa_group_segment_fixed_size 0
		.amdhsa_private_segment_fixed_size 0
		.amdhsa_kernarg_size 376
		.amdhsa_user_sgpr_count 2
		.amdhsa_user_sgpr_dispatch_ptr 0
		.amdhsa_user_sgpr_queue_ptr 0
		.amdhsa_user_sgpr_kernarg_segment_ptr 1
		.amdhsa_user_sgpr_dispatch_id 0
		.amdhsa_user_sgpr_kernarg_preload_length 0
		.amdhsa_user_sgpr_kernarg_preload_offset 0
		.amdhsa_user_sgpr_private_segment_size 0
		.amdhsa_uses_dynamic_stack 0
		.amdhsa_enable_private_segment 0
		.amdhsa_system_sgpr_workgroup_id_x 1
		.amdhsa_system_sgpr_workgroup_id_y 0
		.amdhsa_system_sgpr_workgroup_id_z 0
		.amdhsa_system_sgpr_workgroup_info 0
		.amdhsa_system_vgpr_workitem_id 2
		.amdhsa_next_free_vgpr 251
		.amdhsa_next_free_sgpr 102
		.amdhsa_accum_offset 252
		.amdhsa_reserve_vcc 1
		.amdhsa_float_round_mode_32 0
		.amdhsa_float_round_mode_16_64 0
		.amdhsa_float_denorm_mode_32 3
		.amdhsa_float_denorm_mode_16_64 3
		.amdhsa_dx10_clamp 1
		.amdhsa_ieee_mode 1
		.amdhsa_fp16_overflow 0
		.amdhsa_tg_split 0
		.amdhsa_exception_fp_ieee_invalid_op 0
		.amdhsa_exception_fp_denorm_src 0
		.amdhsa_exception_fp_ieee_div_zero 0
		.amdhsa_exception_fp_ieee_overflow 0
		.amdhsa_exception_fp_ieee_underflow 0
		.amdhsa_exception_fp_ieee_inexact 0
		.amdhsa_exception_int_div_zero 0
	.end_amdhsa_kernel

; __global__ void __launch_bounds__(NTHREADS, 2) fwd(Params p) {
amdhsa.kernels:
  - .agpr_count:     0
    .args:
      - .offset:         0
        .size:           120
        .value_kind:     by_value
      - .offset:         120
        .size:           4
        .value_kind:     hidden_block_count_x
      - .offset:         124
        .size:           4
        .value_kind:     hidden_block_count_y
      - .offset:         128
        .size:           4
        .value_kind:     hidden_block_count_z
      - .offset:         132
        .size:           2
        .value_kind:     hidden_group_size_x
      - .offset:         134
        .size:           2
        .value_kind:     hidden_group_size_y
      - .offset:         136
        .size:           2
        .value_kind:     hidden_group_size_z
      - .offset:         138
        .size:           2
        .value_kind:     hidden_remainder_x
      - .offset:         140
        .size:           2
        .value_kind:     hidden_remainder_y
      - .offset:         142
        .size:           2
        .value_kind:     hidden_remainder_z
      - .offset:         160
        .size:           8
        .value_kind:     hidden_global_offset_x
      - .offset:         168
        .size:           8
        .value_kind:     hidden_global_offset_y
      - .offset:         176
        .size:           8
        .value_kind:     hidden_global_offset_z
      - .offset:         184
        .size:           2
        .value_kind:     hidden_grid_dims
      - .offset:         208
        .size:           8
        .value_kind:     hidden_multigrid_sync_arg
      - .offset:         240
        .size:           4
        .value_kind:     hidden_dynamic_lds_size
    .group_segment_fixed_size: 0
    .kernarg_segment_align: 8
    .kernarg_segment_size: 376
    .language:       OpenCL C
    .language_version:
      - 2
      - 0
    .max_flat_workgroup_size: 512
    .name:           _ZN2mk3fwdENS_6ParamsE
    .private_segment_fixed_size: 0
    .sgpr_count:     108
    .sgpr_spill_count: 137
    .symbol:         _ZN2mk3fwdENS_6ParamsE.kd
    .uniform_work_group_size: 1
    .uses_dynamic_stack: false
    .vgpr_count:     251
    .vgpr_spill_count: 0
    .wavefront_size: 64
